# v18 + ProjB epilogue: gain, cos/sin and row-ssq loads of a tile issued together behind one wait (was two serialized round trips)
# baseline (speedup 1.0000x reference)
; __device__ __forceinline__ float shx(float v, int lane, int mask) { return __int_as_float(__builtin_amdgcn_ds_bpermute((lane ^ mask) << 2, __float_as_int(v))); }
;     __device__ __forceinline__ void operator()(const AccT& acc, const Unit& u, int wr, int wc, int fr, int fq) const {
;     ...
;         float rsn[2]; rsn[0] = ssq[row0]; rsn[1] = ssq[row0 + 16];
;         const bool rope = seg < 2;
;         f32x4 g1a, g1b, g2a, g2b;
;         if (rope) { g1a = *(const f32x4*)(gn); g1b = *(const f32x4*)(gn + 4); g2a = *(const f32x4*)(gn + 64); g2b = *(const f32x4*)(gn + 68); }
;         const int t0 = row0 & (SEQ - 1);
;         const float* cb0 = cosT + (size_t)t0 * 64 + c0; const float* sb0 = sinT + (size_t)t0 * 64 + c0;
;         f32x4 tca, tcb, tsa, tsb;
;         if (rope) { tca = *(const f32x4*)(cb0); tcb = *(const f32x4*)(cb0 + 4); tsa = *(const f32x4*)(sb0); tsb = *(const f32x4*)(sb0 + 4); }
; #pragma unroll
;         for (int idx = 0; idx < 8; ++idx) {
;             const int ai = idx >> 2, m = idx & 3, rofs = ai * 128 + m * 16;
;             const int row = row0 + rofs; const float rs = rsqrtf(rsn[idx & 1] * (1.f / 1024.f) + EPS);
;             if (idx + 2 < 8) rsn[idx & 1] = ssq[row0 + ((idx + 2) >> 2) * 128 + ((idx + 2) & 3) * 16];
;             float v1[8], v2[8];
; #pragma unroll
;             for (int n = 0; n < 2; ++n)
; #pragma unroll
;                 for (int j = 0; j < 4; ++j) { v1[n * 4 + j] = acc[ai][0][m][n][j] * rs; v2[n * 4 + j] = acc[ai][1][m][n][j] * rs; }
;             if (rope) {
;                 float s = 0.f;
; #pragma unroll
;                 for (int e = 0; e < 8; ++e) s += v1[e] * v1[e] + v2[e] * v2[e];
;                 s += shx(s, LANE_, 16); s += shx(s, LANE_, 32);
;                 if (fq == 0) atomicAdd(hssq + (size_t)row * 24 + seg * 12 + head, s);
.LBB0_545:
	v_lshl_add_u32 v182, s35, 8, v169
	v_ashrrev_i32_e32 v183, 31, v182
	v_lshl_add_u64 v[198:199], v[182:183], 2, s[12:13]
	global_load_dword v179, v[198:199], off
	global_load_dword v183, v[198:199], off offset:64
	s_mul_hi_i32 s21, s34, 0x2aaaaaab
	s_lshr_b32 s4, s21, 31
	s_add_i32 s21, s21, s4
	s_mul_i32 s23, s21, -6
	s_add_i32 s23, s23, s34
	s_cmp_lt_i32 s34, 12
	s_cselect_b64 s[28:29], -1, 0
	s_cmp_gt_i32 s34, 11
	s_cbranch_scc1 .LBB0_547
	s_add_i32 s4, s34, 5
	s_cmp_lt_u32 s4, 11
	s_cselect_b32 s5, s8, s10
	s_cselect_b32 s4, s9, s11
	s_add_u32 s30, s5, s18
	s_addc_u32 s31, s4, s19
	s_lshl_b32 s4, s23, 6
	s_and_b32 s4, s4, 0xffffff80
	s_ashr_i32 s5, s4, 31
	s_lshl_b64 s[4:5], s[4:5], 2
	s_add_u32 s4, s30, s4
	s_addc_u32 s5, s31, s5
	v_lshlrev_b32_e32 v56, 2, v168
	global_load_dwordx4 v[48:51], v56, s[4:5] offset:272
	global_load_dwordx4 v[52:55], v56, s[4:5] offset:16
	global_load_dwordx4 v[60:63], v56, s[4:5]
	s_nop 0
	global_load_dwordx4 v[56:59], v56, s[4:5] offset:256
	s_nop 0
	s_nop 0
	s_nop 0
.LBB0_547:
	v_lshlrev_b32_e32 v218, 8, v182
	v_and_b32_e32 v188, 0x1fcf00, v218
	v_cndmask_b32_e64 v218, 0, 1, s[28:29]
	v_lshl_add_u64 v[186:187], v[170:171], 0, v[188:189]
	v_cmp_ne_u32_e64 s[4:5], 1, v218
	s_andn2_b64 vcc, exec, s[28:29]
	v_lshl_add_u64 v[184:185], v[172:173], 0, v[188:189]
	s_cbranch_vccnz .LBB0_549
	global_load_dwordx4 v[64:67], v[186:187], off offset:16
	global_load_dwordx4 v[68:71], v[186:187], off
	global_load_dwordx4 v[88:91], v[184:185], off offset:16
	global_load_dwordx4 v[92:95], v[184:185], off
.LBB0_549:
	global_load_dword v219, v[198:199], off offset:128
	s_waitcnt vmcnt(0)
	v_mov_b32_e32 v181, v51
	v_mov_b32_e32 v180, v55
	v_fmamk_f32 v55, v179, 0x3a800000, v226
	v_mul_f32_e32 v179, 0x4b800000, v55
	v_cmp_gt_f32_e32 vcc, s33, v55
	s_lshl_b32 s23, s23, 1
	s_or_b32 s28, s23, s44
	v_cndmask_b32_e32 v55, v55, v179, vcc
	v_rsq_f32_e32 v55, v55
	s_mul_i32 s30, s21, 12
	s_ashr_i32 s31, s30, 31
	s_ashr_i32 s29, s28, 31
	v_mul_f32_e32 v179, 0x45800000, v55
	v_cndmask_b32_e32 v188, v55, v179, vcc
	v_pk_mul_f32 v[200:201], v[148:149], v[188:189] op_sel_hi:[1,0]
	v_mul_f32_e32 v148, v146, v188
	v_mov_b32_e32 v146, v155
	v_pk_mul_f32 v[204:205], v[156:157], v[188:189] op_sel_hi:[1,0]
	v_pk_mul_f32 v[202:203], v[158:159], v[188:189] op_sel_hi:[1,0]
	v_pk_mul_f32 v[156:157], v[150:151], v[188:189] op_sel_hi:[1,0]
	v_pk_mul_f32 v[158:159], v[152:153], v[188:189] op_sel_hi:[1,0]
	v_pk_mul_f32 v[150:151], v[144:145], v[188:189] op_sel_hi:[1,0]
	v_mul_f32_e32 v152, v154, v188
	s_and_b64 vcc, exec, s[4:5]
	v_pk_mul_f32 v[144:145], v[146:147], v[188:189] op_sel_hi:[1,0]
	s_cbranch_vccnz .LBB0_553
	v_pk_mul_f32 v[146:147], v[200:201], v[200:201]
	v_pk_mul_f32 v[154:155], v[156:157], v[156:157]
	v_pk_fma_f32 v[146:147], v[204:205], v[204:205], v[146:147]
	v_pk_fma_f32 v[154:155], v[202:203], v[202:203], v[154:155]
	v_add_f32_e32 v55, v146, v147
	v_pk_mul_f32 v[210:211], v[150:151], v[150:151]
	v_add_f32_e32 v55, v154, v55
	v_pk_fma_f32 v[210:211], v[158:159], v[158:159], v[210:211]
	v_add_f32_e32 v55, v155, v55
	v_add_f32_e32 v55, v210, v55
	v_mul_f32_e32 v146, v148, v148
	v_add_f32_e32 v55, v211, v55
	v_fmac_f32_e32 v146, v152, v152
	v_add_f32_e32 v55, v146, v55
	v_pk_mul_f32 v[146:147], v[144:145], v[144:145]
	s_nop 0
	v_add_f32_e32 v146, v146, v147
	v_add_f32_e32 v55, v146, v55
	ds_bpermute_b32 v146, v207, v55
	s_waitcnt lgkmcnt(0)
	v_add_f32_e32 v55, v55, v146
	ds_bpermute_b32 v146, v208, v55
	s_and_saveexec_b64 s[34:35], s[0:1]
	s_cbranch_execz .LBB0_552
	s_waitcnt lgkmcnt(0)
	v_add_f32_e32 v55, v55, v146
	v_mov_b64_e32 v[146:147], s[14:15]
	v_mad_i64_i32 v[146:147], s[50:51], v182, s63, v[146:147]
	v_lshl_add_u64 v[146:147], s[30:31], 2, v[146:147]
	v_lshl_add_u64 v[146:147], s[28:29], 2, v[146:147]
	global_atomic_add_f32 v[146:147], v55, off

; __device__ __forceinline__ unsigned pk2(float lo, float hi) { f32x2 v = {lo, hi}; bf2_t b = __builtin_convertvector(v, bf2_t); return __builtin_bit_cast(unsigned, b); }
; __device__ __forceinline__ float shx(float v, int lane, int mask) { return __int_as_float(__builtin_amdgcn_ds_bpermute((lane ^ mask) << 2, __float_as_int(v))); }
;     __device__ __forceinline__ void operator()(const AccT& acc, const Unit& u, int wr, int wc, int fr, int fq) const {
;     ...
;             const int row = row0 + rofs; const float rs = rsqrtf(rsn[idx & 1] * (1.f / 1024.f) + EPS);
;             if (idx + 2 < 8) rsn[idx & 1] = ssq[row0 + ((idx + 2) >> 2) * 128 + ((idx + 2) & 3) * 16];
;             float v1[8], v2[8];
; #pragma unroll
;             for (int n = 0; n < 2; ++n)
; #pragma unroll
;                 for (int j = 0; j < 4; ++j) { v1[n * 4 + j] = acc[ai][0][m][n][j] * rs; v2[n * 4 + j] = acc[ai][1][m][n][j] * rs; }
;             if (rope) {
;                 float s = 0.f;
; #pragma unroll
;                 for (int e = 0; e < 8; ++e) s += v1[e] * v1[e] + v2[e] * v2[e];
;                 s += shx(s, LANE_, 16); s += shx(s, LANE_, 32);
;                 if (fq == 0) atomicAdd(hssq + (size_t)row * 24 + seg * 12 + head, s);
;     ...
;             u32x4 w1, w2; w1.x = pk2(v1[0], v1[1]); w1.y = pk2(v1[2], v1[3]); w1.z = pk2(v1[4], v1[5]); w1.w = pk2(v1[6], v1[7]);
;             w2.x = pk2(v2[0], v2[1]); w2.y = pk2(v2[2], v2[3]); w2.z = pk2(v2[4], v2[5]); w2.w = pk2(v2[6], v2[7]);
;             bf16_t* p = base + (size_t)row * ATW + head * 128 + c0;
;             *(u32x4*)p = w1; *(u32x4*)(p + 64) = w2;
.LBB0_559:
	v_cvt_pk_bf16_f32 v152, v148, v149
	v_cvt_pk_bf16_f32 v153, v146, v147
	v_cvt_pk_bf16_f32 v154, v142, v143
	v_cvt_pk_bf16_f32 v155, v136, v137
	v_cvt_pk_bf16_f32 v132, v132, v133
	v_cvt_pk_bf16_f32 v133, v128, v129
	v_mad_i64_i32 v[128:129], s[34:35], v55, s80, v[144:145]
	v_cvt_pk_bf16_f32 v130, v140, v141
	v_cvt_pk_bf16_f32 v131, v134, v135
	global_store_dwordx4 v[128:129], v[152:155], off
	global_store_dwordx4 v[128:129], v[130:133], off offset:128
	global_load_dword v55, v[198:199], off offset:512
	v_fmamk_f32 v51, v219, 0x3a800000, v226
	v_mul_f32_e32 v128, 0x4b800000, v51
	v_cmp_gt_f32_e32 vcc, s33, v51
	s_nop 1
	v_cndmask_b32_e32 v51, v51, v128, vcc
	v_rsq_f32_e32 v128, v51
	v_or_b32_e32 v51, 32, v182
	v_mul_f32_e32 v129, 0x45800000, v128
	v_cndmask_b32_e32 v132, v128, v129, vcc
	v_pk_mul_f32 v[130:131], v[124:125], v[132:133] op_sel_hi:[1,0]
	v_pk_mul_f32 v[124:125], v[116:117], v[132:133] op_sel_hi:[1,0]
	v_pk_mul_f32 v[116:117], v[112:113], v[132:133] op_sel_hi:[1,0]
	v_mul_f32_e32 v112, v114, v132
	v_mov_b32_e32 v114, v123
	v_pk_mul_f32 v[128:129], v[126:127], v[132:133] op_sel_hi:[1,0]
	v_pk_mul_f32 v[118:119], v[118:119], v[132:133] op_sel_hi:[1,0]
	v_pk_mul_f32 v[126:127], v[120:121], v[132:133] op_sel_hi:[1,0]
	v_mul_f32_e32 v120, v122, v132
	s_and_b64 vcc, exec, s[4:5]
	v_pk_mul_f32 v[114:115], v[114:115], v[132:133] op_sel_hi:[1,0]
	s_cbranch_vccnz .LBB0_563
	v_pk_mul_f32 v[122:123], v[124:125], v[124:125]
	v_pk_mul_f32 v[132:133], v[118:119], v[118:119]
	v_pk_fma_f32 v[122:123], v[130:131], v[130:131], v[122:123]
	v_pk_fma_f32 v[132:133], v[128:129], v[128:129], v[132:133]
	v_add_f32_e32 v113, v122, v123
	v_pk_mul_f32 v[134:135], v[116:117], v[116:117]
	v_add_f32_e32 v113, v132, v113
	v_pk_fma_f32 v[134:135], v[126:127], v[126:127], v[134:135]
	v_add_f32_e32 v113, v133, v113
	v_add_f32_e32 v113, v134, v113
	v_mul_f32_e32 v121, v112, v112
	v_add_f32_e32 v113, v135, v113
	v_fmac_f32_e32 v121, v120, v120
	v_pk_mul_f32 v[122:123], v[114:115], v[114:115]
	v_add_f32_e32 v113, v121, v113
	v_add_f32_e32 v121, v122, v123
	v_add_f32_e32 v113, v121, v113
	ds_bpermute_b32 v121, v207, v113
	s_waitcnt lgkmcnt(0)
	v_add_f32_e32 v113, v113, v121
	ds_bpermute_b32 v121, v208, v113
	s_and_saveexec_b64 s[34:35], s[0:1]
	s_cbranch_execz .LBB0_562
	v_mov_b64_e32 v[122:123], s[14:15]
	v_mad_i64_i32 v[122:123], s[50:51], v51, s63, v[122:123]
	v_lshl_add_u64 v[122:123], s[30:31], 2, v[122:123]
	s_waitcnt lgkmcnt(0)
	v_add_f32_e32 v113, v113, v121
	v_lshl_add_u64 v[122:123], s[28:29], 2, v[122:123]
	global_atomic_add_f32 v[122:123], v113, off
